# It-A hoisted LDS fragment reads issued before the scalar DMA address block
# speedup vs baseline: 1.0579x; 1.0050x over previous
.LBB0_832:
	s_andn2_b64 vcc, exec, s[0:1]
	s_cbranch_vccnz .LBB0_834
	s_add_i32 s9, s78, 0x10000
	s_and_b32 s33, s9, 0x18000
	s_and_b32 s76, s78, 0x18000
	v_add_u32_e32 v250, s33, v237
	v_add_u32_e32 v250, v250, v228
	ds_read_b128 v[128:131], v250 offset:16384
	ds_read_b128 v[132:135], v250 offset:20480
	ds_read_b128 v[136:139], v250 offset:24576
	ds_read_b128 v[140:143], v250 offset:28672
	v_add_u32_e32 v251, s76, v235
	v_add_u32_e32 v250, v251, v228
	ds_read_b128 v[144:147], v250
	ds_read_b128 v[148:151], v250 offset:4096
	v_add_u32_e32 v250, v251, v231
	ds_read_b128 v[152:155], v250
	ds_read_b128 v[156:159], v250 offset:4096
	s_add_i32 s0, s74, s38
	s_addk_i32 s0, 0xc0
	s_mul_i32 s0, s0, s14
	s_lshl_b32 s92, s46, 1
	s_add_i32 s0, s0, s92
	s_addk_i32 s0, 0x1c00
	s_add_u32 s98, s82, s0
	s_addc_u32 s99, s83, 0
	s_add_i32 s0, s78, 0x8000
	s_and_b32 s0, s0, 0x18000
	s_add_i32 s0, s5, s0
	s_mov_b32 m0, s0
	s_nop 0
	global_load_lds_dwordx4 v244, s[98:99]
	s_add_i32 m0, s0, 0x2000
	s_add_u32 s98, s98, 0x80
	s_addc_u32 s99, s99, 0
	global_load_lds_dwordx4 v244, s[98:99]
	s_lshl_b32 s1, s17, 13
	s_add_u32 s98, s40, s1
	s_addc_u32 s99, s41, 0
	s_add_i32 m0, s0, 0x4000
	s_nop 0
	global_load_lds_dwordx4 v245, s[98:99]
	s_add_i32 m0, s0, 0x6000
	s_add_u32 s98, s98, 0x80000
	s_addc_u32 s99, s99, 0
	global_load_lds_dwordx4 v245, s[98:99]
	v_max3_f32 v246, v64, v65, v66
	v_max3_f32 v247, v72, v73, v74
	v_max3_f32 v248, v80, v81, v82
	v_max3_f32 v249, v88, v89, v90
	v_max3_f32 v246, v246, v67, v68
	v_max3_f32 v247, v247, v75, v76
	v_max3_f32 v248, v248, v83, v84
	v_max3_f32 v249, v249, v91, v92
	s_waitcnt lgkmcnt(7)
	v_mfma_f32_32x32x16_bf16 v[0:15], v[128:131], v[96:99], v[0:15]
	v_max3_f32 v246, v246, v69, v70
	v_max3_f32 v247, v247, v77, v78
	v_max3_f32 v248, v248, v85, v86
	v_max3_f32 v249, v249, v93, v94
	v_max3_f32 v246, v246, v71, v247
	v_max3_f32 v247, v248, v87, v249
	v_max_f32_e32 v248, v212, v212
	s_waitcnt lgkmcnt(6)
	v_mfma_f32_32x32x16_bf16 v[48:63], v[132:135], v[96:99], v[48:63]
	v_max3_f32 v246, v246, v79, v95
	s_nop 0
	v_max3_f32 v246, v246, v247, v247
	s_nop 0
	v_mov_b32_e32 v247, v246
	s_nop 1
	v_permlane32_swap_b32_e32 v246, v247
	v_max3_f32 v246, v246, v247, v247
	s_nop 0
	v_max_f32_e32 v247, v246, v246
	v_max_f32_e32 v251, v248, v247
	s_waitcnt lgkmcnt(5)
	v_mfma_f32_32x32x16_bf16 v[32:47], v[136:139], v[96:99], v[32:47]
	v_sub_f32_e32 v247, v212, v251
	v_exp_f32_e32 v250, v247
	v_add_f32_e32 v247, 0x41000000, v212
	v_cmp_gt_f32_e32 vcc, v246, v247
	s_cmp_eq_u64 vcc, 0
	v_mul_f32_e32 v246, v100, v250
	s_cselect_b64 s[0:1], -1, 0
	v_cndmask_b32_e64 v194, v246, v100, s[0:1]
	s_waitcnt lgkmcnt(4)
	v_mfma_f32_32x32x16_bf16 v[16:31], v[140:143], v[96:99], v[16:31]
	v_cndmask_b32_e64 v212, v251, v212, s[0:1]
	v_mov_b32_e32 v213, v212
	v_sub_f32_e32 v140, v92, v212
	v_sub_f32_e32 v141, v93, v213
	v_sub_f32_e32 v138, v90, v212
	v_sub_f32_e32 v139, v91, v213
	s_waitcnt lgkmcnt(3)
	v_mfma_f32_32x32x16_bf16 v[96:111], v[144:147], v[160:163], 0
	v_sub_f32_e32 v142, v94, v212
	v_sub_f32_e32 v143, v95, v213
	v_sub_f32_e32 v92, v80, v212
	v_sub_f32_e32 v93, v81, v213
	v_sub_f32_e32 v128, v82, v212
	v_sub_f32_e32 v129, v83, v213
	s_waitcnt lgkmcnt(2)
	v_mfma_f32_32x32x16_bf16 v[112:127], v[148:151], v[160:163], 0
	v_sub_f32_e32 v130, v68, v212
	v_sub_f32_e32 v131, v69, v213
	v_sub_f32_e32 v90, v64, v212
	v_sub_f32_e32 v91, v65, v213
	v_sub_f32_e32 v132, v84, v212
	v_sub_f32_e32 v133, v85, v213
	s_waitcnt lgkmcnt(1)
	v_mfma_f32_32x32x16_bf16 v[96:111], v[152:155], v[164:167], v[96:111]
	v_sub_f32_e32 v94, v66, v212
	v_sub_f32_e32 v95, v67, v213
	v_sub_f32_e32 v134, v86, v212
	v_sub_f32_e32 v135, v87, v213
	v_sub_f32_e32 v136, v88, v212
	v_sub_f32_e32 v137, v89, v213
	s_waitcnt lgkmcnt(0)
	v_mfma_f32_32x32x16_bf16 v[112:127], v[156:159], v[164:167], v[112:127]
	v_sub_f32_e32 v144, v70, v212
	v_sub_f32_e32 v145, v71, v213
	v_sub_f32_e32 v148, v74, v212
	v_sub_f32_e32 v149, v75, v213
	v_sub_f32_e32 v150, v76, v212
	v_sub_f32_e32 v151, v77, v213
	v_sub_f32_e32 v146, v72, v212
	v_sub_f32_e32 v147, v73, v213
	v_sub_f32_e32 v152, v78, v212
	v_sub_f32_e32 v153, v79, v213
	v_mov_b32_e32 v68, v250
	s_branch .Lattn_body_1

.LBB0_862:
	s_andn2_b64 vcc, exec, s[0:1]
	s_cbranch_vccnz .LBB0_864
	s_add_i32 s9, s34, 0x10000
	s_and_b32 s33, s9, 0x18000
	s_and_b32 s10, s34, 0x18000
	v_add_u32_e32 v250, s33, v237
	v_add_u32_e32 v250, v250, v230
	ds_read_b128 v[128:131], v250 offset:16384
	ds_read_b128 v[132:135], v250 offset:20480
	ds_read_b128 v[136:139], v250 offset:24576
	ds_read_b128 v[140:143], v250 offset:28672
	v_add_u32_e32 v251, s10, v236
	v_add_u32_e32 v250, v251, v230
	ds_read_b128 v[144:147], v250
	ds_read_b128 v[148:151], v250 offset:4096
	v_add_u32_e32 v250, v251, v233
	ds_read_b128 v[152:155], v250
	ds_read_b128 v[156:159], v250 offset:4096
	s_add_i32 s0, s74, s64
	s_addk_i32 s0, 0xc0
	s_mul_i32 s0, s0, s14
	s_add_i32 s0, s0, s92
	s_addk_i32 s0, 0x1c00
	s_add_u32 s98, s82, s0
	s_addc_u32 s99, s83, 0
	s_lshl_b32 s1, s17, 13
	s_add_u32 s46, s76, s1
	s_addc_u32 s47, s77, 0
	s_add_i32 s0, s34, 0x8000
	s_and_b32 s0, s0, 0x18000
	s_add_i32 s0, s5, s0
	s_mov_b32 m0, s0
	s_nop 0
	global_load_lds_dwordx4 v244, s[98:99]
	s_add_i32 m0, s0, 0x2000
	s_add_u32 s98, s98, 0x80
	s_addc_u32 s99, s99, 0
	global_load_lds_dwordx4 v244, s[98:99]
	s_add_i32 m0, s0, 0x4000
	s_nop 0
	global_load_lds_dwordx4 v245, s[46:47]
	s_add_i32 m0, s0, 0x6000
	s_add_u32 s46, s46, 0x80000
	s_addc_u32 s47, s47, 0
	global_load_lds_dwordx4 v245, s[46:47]
	v_max3_f32 v246, v64, v65, v66
	v_max3_f32 v247, v72, v73, v74
	v_max3_f32 v248, v80, v81, v82
	v_max3_f32 v249, v88, v89, v90
	v_max3_f32 v246, v246, v67, v68
	v_max3_f32 v247, v247, v75, v76
	v_max3_f32 v248, v248, v83, v84
	v_max3_f32 v249, v249, v91, v92
	s_waitcnt lgkmcnt(7)
	v_mfma_f32_32x32x16_bf16 v[0:15], v[128:131], v[96:99], v[0:15]
	v_max3_f32 v246, v246, v69, v70
	v_max3_f32 v247, v247, v77, v78
	v_max3_f32 v248, v248, v85, v86
	v_max3_f32 v249, v249, v93, v94
	v_max3_f32 v246, v246, v71, v247
	v_max3_f32 v247, v248, v87, v249
	v_max_f32_e32 v248, v214, v214
	s_waitcnt lgkmcnt(6)
	v_mfma_f32_32x32x16_bf16 v[48:63], v[132:135], v[96:99], v[48:63]
	v_max3_f32 v246, v246, v79, v95
	s_nop 0
	v_max3_f32 v246, v246, v247, v247
	s_nop 0
	v_mov_b32_e32 v247, v246
	s_nop 1
	v_permlane32_swap_b32_e32 v246, v247
	v_max3_f32 v246, v246, v247, v247
	s_nop 0
	v_max_f32_e32 v247, v246, v246
	v_max_f32_e32 v251, v248, v247
	s_waitcnt lgkmcnt(5)
	v_mfma_f32_32x32x16_bf16 v[32:47], v[136:139], v[96:99], v[32:47]
	v_sub_f32_e32 v247, v214, v251
	v_exp_f32_e32 v250, v247
	v_add_f32_e32 v247, 0x41000000, v214
	v_cmp_gt_f32_e32 vcc, v246, v247
	s_cmp_eq_u64 vcc, 0
	v_mul_f32_e32 v246, v100, v250
	s_cselect_b64 s[0:1], -1, 0
	v_cndmask_b32_e64 v194, v246, v100, s[0:1]
	s_waitcnt lgkmcnt(4)
	v_mfma_f32_32x32x16_bf16 v[16:31], v[140:143], v[96:99], v[16:31]
	v_cndmask_b32_e64 v214, v251, v214, s[0:1]
	v_mov_b32_e32 v215, v214
	v_sub_f32_e32 v140, v92, v214
	v_sub_f32_e32 v141, v93, v215
	v_sub_f32_e32 v138, v90, v214
	v_sub_f32_e32 v139, v91, v215
	s_waitcnt lgkmcnt(3)
	v_mfma_f32_32x32x16_bf16 v[96:111], v[144:147], v[160:163], 0
	v_sub_f32_e32 v142, v94, v214
	v_sub_f32_e32 v143, v95, v215
	v_sub_f32_e32 v92, v80, v214
	v_sub_f32_e32 v93, v81, v215
	v_sub_f32_e32 v128, v82, v214
	v_sub_f32_e32 v129, v83, v215
	s_waitcnt lgkmcnt(2)
	v_mfma_f32_32x32x16_bf16 v[112:127], v[148:151], v[160:163], 0
	v_sub_f32_e32 v130, v68, v214
	v_sub_f32_e32 v131, v69, v215
	v_sub_f32_e32 v90, v64, v214
	v_sub_f32_e32 v91, v65, v215
	v_sub_f32_e32 v132, v84, v214
	v_sub_f32_e32 v133, v85, v215
	s_waitcnt lgkmcnt(1)
	v_mfma_f32_32x32x16_bf16 v[96:111], v[152:155], v[164:167], v[96:111]
	v_sub_f32_e32 v94, v66, v214
	v_sub_f32_e32 v95, v67, v215
	v_sub_f32_e32 v134, v86, v214
	v_sub_f32_e32 v135, v87, v215
	v_sub_f32_e32 v136, v88, v214
	v_sub_f32_e32 v137, v89, v215
	s_waitcnt lgkmcnt(0)
	v_mfma_f32_32x32x16_bf16 v[112:127], v[156:159], v[164:167], v[112:127]
	v_sub_f32_e32 v144, v70, v214
	v_sub_f32_e32 v145, v71, v215
	v_sub_f32_e32 v148, v74, v214
	v_sub_f32_e32 v149, v75, v215
	v_sub_f32_e32 v150, v76, v214
	v_sub_f32_e32 v151, v77, v215
	v_sub_f32_e32 v146, v72, v214
	v_sub_f32_e32 v147, v73, v215
	v_sub_f32_e32 v152, v78, v214
	v_sub_f32_e32 v153, v79, v215
	v_mov_b32_e32 v68, v250
	s_branch .Lattn_body_2
